# P6 tail round removed: last 16 tiles cut into 256 16-row sub-tiles (one per workgroup, direct global->VGPR MFMA operands)
# speedup vs baseline: 1.0094x; 1.0037x over previous
.LBB0_1008:
	s_add_u32 s6, s84, 0x2300000
	s_addc_u32 s7, s85, 0
	s_add_u32 s8, s84, 0x2d300000
	v_readlane_b32 s10, v255, 6
	s_addc_u32 s9, s85, 0
	v_readlane_b32 s11, v255, 7
	s_lshl_b32 s10, s10, 5
	s_and_b32 s16, s10, 0x60
	s_mov_b64 s[10:11], 0x80
	s_add_i32 m0, s27, 0x18000
	v_lshl_add_u64 v[6:7], v[6:7], 0, s[10:11]
	s_lshl_b32 s1, s0, 13
	s_lshr_b32 s15, s16, 3
	s_waitcnt vmcnt(2)
	s_barrier
	global_load_lds_dwordx4 v[6:7], off
	v_lshl_add_u64 v[4:5], v[4:5], 0, s[10:11]
	s_add_i32 m0, s27, 0x1a000
	s_add_i32 s42, s27, 0x8000
	s_add_i32 s43, s27, 0xa000
	global_load_lds_dwordx4 v[4:5], off
	v_lshl_add_u64 v[0:1], v[0:1], 0, s[10:11]
	s_mov_b32 m0, s42
	s_add_u32 s12, s28, 0x40080
	global_load_lds_dwordx4 v[0:1], off
	v_lshl_add_u64 v[0:1], v[2:3], 0, s[10:11]
	s_mov_b32 m0, s43
	s_addc_u32 s13, s29, 0
	global_load_lds_dwordx4 v[0:1], off
	s_add_i32 m0, s27, 0x1c000
	v_lshl_add_u64 v[0:1], s[12:13], 0, v[132:133]
	global_load_lds_dwordx4 v[0:1], off
	v_lshl_add_u64 v[0:1], s[12:13], 0, v[128:129]
	s_add_i32 m0, s27, 0x1e000
	v_and_b32_e32 v3, 48, v9
	global_load_lds_dwordx4 v[0:1], off
	v_and_b32_e32 v0, 15, v9
	v_lshl_or_b32 v152, s0, 6, v0
	v_ashrrev_i32_e32 v2, 6, v9
	v_lshl_or_b32 v0, v0, 6, v3
	v_lshlrev_b32_e32 v3, 2, v9
	v_lshl_add_u32 v4, v2, 10, s1
	v_and_b32_e32 v3, 32, v3
	v_add_lshl_u32 v2, v2, s15, 10
	v_ashrrev_i32_e32 v1, 1, v9
	v_bitop3_b32 v4, v0, v4, v3 bitop3:0xde
	v_bitop3_b32 v153, v0, v2, v3 bitop3:0xde
	v_lshlrev_b32_e32 v0, 14, v12
	v_and_b32_e32 v1, -8, v1
	v_and_b32_e32 v0, 0xffff8000, v0
	v_readlane_b32 s12, v255, 0
	v_add_u32_e32 v154, s16, v1
	v_lshl_add_u32 v0, v13, 11, v0
	v_and_b32_e32 v1, 1, v12
	v_readlane_b32 s13, v255, 1
	v_lshl_or_b32 v0, v1, 6, v0
	s_load_dwordx2 s[12:13], s[12:13], 0xc8
	v_lshl_add_u32 v136, v14, 1, v0
	v_lshlrev_b32_e32 v0, 14, v8
	v_and_b32_e32 v0, 0xffff8000, v0
	s_waitcnt vmcnt(6)
	s_cmpk_lt_u32 s82, 0x100
	v_lshl_add_u32 v0, v10, 11, v0
	v_and_b32_e32 v1, 1, v8
	s_sext_i32_i8 s48, s14
	s_cselect_b64 s[14:15], -1, 0
	v_lshl_or_b32 v0, v1, 6, v0
	s_add_i32 s45, 0, 0x10000
	s_add_i32 s46, 0, 0x14000
	s_ashr_i32 s44, s67, 31
	v_mov_b32_e32 v137, v133
	v_lshl_add_u32 v138, v11, 1, v0
	v_mov_b32_e32 v139, v133
	v_mov_b64_e32 v[140:141], 0x400
	v_mov_b64_e32 v[142:143], 0x3ff
	v_add_u32_e32 v155, s45, v153
	v_add_u32_e32 v156, s46, v153
	v_add_u32_e32 v157, 0, v4
	v_mov_b32_e32 v158, 0x358637bd
	s_mov_b32 s47, 0x800000
	s_barrier
	v_lshl_add_u32 v144, s26, 8, v152
	v_mov_b32_e32 v145, 0
	v_lshlrev_b64 v[144:145], 6, v[144:145]
	v_and_b32_e32 v146, 24, v154
	v_lshlrev_b32_e32 v146, 1, v146
	v_mov_b32_e32 v147, 0
	v_lshl_add_u64 v[144:145], s[6:7], 0, v[144:145]
	v_lshl_add_u64 v[144:145], v[144:145], 0, v[146:147]
	global_load_dwordx4 v[112:115], v[144:145], off
	global_load_dwordx4 v[116:119], v[144:145], off offset:1024
	global_load_dwordx4 v[120:123], v[144:145], off offset:2048
	global_load_dwordx4 v[124:127], v[144:145], off offset:3072
	v_add_co_u32_e32 v144, vcc, 0x2000, v144
	s_nop 1
	v_addc_co_u32_e32 v145, vcc, 0, v145, vcc
	global_load_dwordx4 v[96:99], v[144:145], off
	global_load_dwordx4 v[100:103], v[144:145], off offset:1024
	global_load_dwordx4 v[104:107], v[144:145], off offset:2048
	global_load_dwordx4 v[108:111], v[144:145], off offset:3072
	s_waitcnt vmcnt(0)
	v_add_f32_e32 v112, v112, v113
	v_add_f32_e32 v116, v116, v117
	v_add_f32_e32 v120, v120, v121
	v_add_f32_e32 v124, v124, v125
	v_add_f32_e32 v96, v96, v97
	v_add_f32_e32 v100, v100, v101
	v_add_f32_e32 v104, v104, v105
	v_add_f32_e32 v108, v108, v109
	v_add_f32_e32 v114, v114, v115
	v_add_f32_e32 v118, v118, v119
	v_add_f32_e32 v122, v122, v123
	v_add_f32_e32 v126, v126, v127
	v_add_f32_e32 v98, v98, v99
	v_add_f32_e32 v102, v102, v103
	v_add_f32_e32 v106, v106, v107
	v_add_f32_e32 v110, v110, v111
	v_add_f32_e32 v112, v112, v114
	v_add_f32_e32 v116, v116, v118
	v_add_f32_e32 v120, v120, v122
	v_add_f32_e32 v124, v124, v126
	v_add_f32_e32 v96, v96, v98
	v_add_f32_e32 v100, v100, v102
	v_add_f32_e32 v104, v104, v106
	v_add_f32_e32 v108, v108, v110
	v_mov_b32_e32 v113, v112
	v_mov_b32_e32 v117, v116
	v_mov_b32_e32 v121, v120
	v_mov_b32_e32 v125, v124
	v_mov_b32_e32 v97, v96
	v_mov_b32_e32 v101, v100
	v_mov_b32_e32 v105, v104
	v_mov_b32_e32 v109, v108
	v_permlane16_swap_b32_e32 v113, v112
	v_permlane16_swap_b32_e32 v117, v116
	v_permlane16_swap_b32_e32 v121, v120
	v_permlane16_swap_b32_e32 v125, v124
	v_permlane16_swap_b32_e32 v97, v96
	v_permlane16_swap_b32_e32 v101, v100
	v_permlane16_swap_b32_e32 v105, v104
	v_permlane16_swap_b32_e32 v109, v108
	v_add_f32_e32 v112, v112, v113
	v_add_f32_e32 v116, v116, v117
	v_add_f32_e32 v120, v120, v121
	v_add_f32_e32 v124, v124, v125
	v_add_f32_e32 v96, v96, v97
	v_add_f32_e32 v100, v100, v101
	v_add_f32_e32 v104, v104, v105
	v_add_f32_e32 v108, v108, v109
	v_mov_b32_e32 v113, v112
	v_mov_b32_e32 v117, v116
	v_mov_b32_e32 v121, v120
	v_mov_b32_e32 v125, v124
	v_mov_b32_e32 v97, v96
	v_mov_b32_e32 v101, v100
	v_mov_b32_e32 v105, v104
	v_mov_b32_e32 v109, v108
	v_permlane32_swap_b32_e32 v113, v112
	v_permlane32_swap_b32_e32 v117, v116
	v_permlane32_swap_b32_e32 v121, v120
	v_permlane32_swap_b32_e32 v125, v124
	v_permlane32_swap_b32_e32 v97, v96
	v_permlane32_swap_b32_e32 v101, v100
	v_permlane32_swap_b32_e32 v105, v104
	v_permlane32_swap_b32_e32 v109, v108
	v_add_f32_e32 v112, v112, v113
	v_add_f32_e32 v116, v116, v117
	v_add_f32_e32 v120, v120, v121
	v_add_f32_e32 v124, v124, v125
	v_add_f32_e32 v96, v96, v97
	v_add_f32_e32 v100, v100, v101
	v_add_f32_e32 v104, v104, v105
	v_add_f32_e32 v108, v108, v109
	v_fmamk_f32 v112, v112, 0x3a800000, v158
	v_fmamk_f32 v116, v116, 0x3a800000, v158
	v_fmamk_f32 v120, v120, 0x3a800000, v158
	v_fmamk_f32 v124, v124, 0x3a800000, v158
	v_fmamk_f32 v96, v96, 0x3a800000, v158
	v_fmamk_f32 v100, v100, 0x3a800000, v158
	v_fmamk_f32 v104, v104, 0x3a800000, v158
	v_fmamk_f32 v108, v108, 0x3a800000, v158
	v_rsq_f32_e32 v226, v112
	v_rsq_f32_e32 v228, v116
	v_rsq_f32_e32 v230, v120
	v_rsq_f32_e32 v232, v124
	v_rsq_f32_e32 v234, v96
	v_rsq_f32_e32 v236, v100
	v_rsq_f32_e32 v238, v104
	v_rsq_f32_e32 v240, v108
	s_branch .LBB0_1011

.LBB0_1020:
	s_waitcnt vmcnt(0)
	s_barrier
	s_mov_b64 exec, -1
	v_readlane_b32 s6, v255, 6
	v_readlane_b32 s8, v255, 0
	v_readlane_b32 s9, v255, 1
	s_nop 4
	s_load_dwordx2 s[12:13], s[8:9], 0xc8
	s_lshr_b32 s0, s59, 4
	s_and_b32 s1, s59, 15
	s_and_b32 s2, s0, 7
	s_lshr_b32 s3, s0, 3
	s_mul_i32 s4, s2, 34
	s_add_i32 s4, s4, 32
	s_add_i32 s5, s4, -8
	s_cmp_gt_u32 s2, 3
	s_cselect_b32 s4, s5, s4
	s_cselect_b32 s5, 1, 0
	s_cmp_eq_u32 s2, 7
	s_cselect_b32 s4, 0x102, s4
	s_cselect_b32 s5, 3, s5
	s_add_i32 s4, s4, s3
	s_lshl_b32 s7, s4, 8
	s_lshl_b32 s10, s1, 4
	s_add_i32 s7, s7, s10
	s_lshr_b32 s10, s6, 2
	s_lshl_b32 s10, s10, 7
	s_and_b32 s11, s6, 3
	s_lshl_b32 s11, s11, 5
	s_lshl_b32 s14, s5, 8
	s_add_i32 s14, s14, s10
	s_add_i32 s14, s14, s11
	s_add_u32 s16, s84, 0x2800000
	s_addc_u32 s17, s85, 0
	s_add_u32 s18, s84, 0x1a00000
	s_addc_u32 s19, s85, 0
	s_add_u32 s20, s84, 0x2300000
	s_addc_u32 s21, s85, 0
	s_add_u32 s22, s84, 0x2d300000
	s_addc_u32 s23, s85, 0
	v_mbcnt_lo_u32_b32 v0, -1, 0
	v_mbcnt_hi_u32_b32 v0, -1, v0
	v_and_b32_e32 v1, 15, v0
	v_lshrrev_b32_e32 v2, 4, v0
	v_add_u32_e32 v3, s7, v1
	v_lshlrev_b32_e32 v6, 11, v3
	v_lshl_add_u32 v6, v2, 4, v6
	v_mov_b32_e32 v7, 0
	v_lshl_add_u64 v[4:5], s[16:17], 0, v[6:7]
	v_lshrrev_b32_e32 v8, 2, v1
	v_lshlrev_b32_e32 v8, 3, v8
	v_and_b32_e32 v9, 3, v1
	v_add3_u32 v8, v8, v9, s14
	v_lshlrev_b32_e32 v10, 11, v8
	v_lshl_add_u32 v10, v2, 4, v10
	v_mov_b32_e32 v11, 0
	v_lshl_add_u64 v[12:13], s[18:19], 0, v[10:11]
	s_mov_b64 s[24:25], 0x2000
	v_lshl_add_u64 v[14:15], v[12:13], 0, s[24:25]
	v_lshlrev_b32_e32 v8, 6, v3
	v_lshl_add_u32 v8, v2, 4, v8
	v_mov_b32_e32 v9, 0
	v_lshl_add_u64 v[8:9], s[20:21], 0, v[8:9]
	global_load_dwordx4 v[216:219], v[8:9], off
	v_lshl_add_u32 v10, v2, 3, s14
	v_lshlrev_b32_e32 v6, 11, v3
	v_lshl_add_u32 v6, v10, 1, v6
	v_lshl_add_u64 v[8:9], s[16:17], 0, v[6:7]
	global_load_dwordx4 v[220:223], v[8:9], off
	v_lshl_add_u64 v[8:9], s[22:23], 0, v[6:7]
	global_load_dwordx4 v[224:227], v[8:9], off nt
	v_lshlrev_b32_e32 v6, 12, v3
	v_lshl_add_u32 v6, v10, 2, v6
	v_mov_b32_e32 v208, 0
	v_mov_b32_e32 v209, 0
	v_mov_b32_e32 v210, 0
	v_mov_b32_e32 v211, 0
	v_mov_b32_e32 v212, 0
	v_mov_b32_e32 v213, 0
	v_mov_b32_e32 v214, 0
	v_mov_b32_e32 v215, 0
	global_load_dwordx4 v[16:19], v[4:5], off
	global_load_dwordx4 v[20:23], v[12:13], off
	global_load_dwordx4 v[24:27], v[14:15], off
	global_load_dwordx4 v[28:31], v[4:5], off offset:64
	global_load_dwordx4 v[32:35], v[12:13], off offset:64
	global_load_dwordx4 v[36:39], v[14:15], off offset:64
	global_load_dwordx4 v[40:43], v[4:5], off offset:128
	global_load_dwordx4 v[44:47], v[12:13], off offset:128
	global_load_dwordx4 v[48:51], v[14:15], off offset:128
	global_load_dwordx4 v[52:55], v[4:5], off offset:192
	global_load_dwordx4 v[56:59], v[12:13], off offset:192
	global_load_dwordx4 v[60:63], v[14:15], off offset:192
	global_load_dwordx4 v[64:67], v[4:5], off offset:256
	global_load_dwordx4 v[68:71], v[12:13], off offset:256
	global_load_dwordx4 v[72:75], v[14:15], off offset:256
	global_load_dwordx4 v[76:79], v[4:5], off offset:320
	global_load_dwordx4 v[80:83], v[12:13], off offset:320
	global_load_dwordx4 v[84:87], v[14:15], off offset:320
	global_load_dwordx4 v[88:91], v[4:5], off offset:384
	global_load_dwordx4 v[92:95], v[12:13], off offset:384
	global_load_dwordx4 v[96:99], v[14:15], off offset:384
	global_load_dwordx4 v[100:103], v[4:5], off offset:448
	global_load_dwordx4 v[104:107], v[12:13], off offset:448
	global_load_dwordx4 v[108:111], v[14:15], off offset:448
	global_load_dwordx4 v[112:115], v[4:5], off offset:512
	global_load_dwordx4 v[116:119], v[12:13], off offset:512
	global_load_dwordx4 v[120:123], v[14:15], off offset:512
	global_load_dwordx4 v[124:127], v[4:5], off offset:576
	global_load_dwordx4 v[128:131], v[12:13], off offset:576
	global_load_dwordx4 v[132:135], v[14:15], off offset:576
	global_load_dwordx4 v[136:139], v[4:5], off offset:640
	global_load_dwordx4 v[140:143], v[12:13], off offset:640
	global_load_dwordx4 v[144:147], v[14:15], off offset:640
	global_load_dwordx4 v[148:151], v[4:5], off offset:704
	global_load_dwordx4 v[152:155], v[12:13], off offset:704
	global_load_dwordx4 v[156:159], v[14:15], off offset:704
	global_load_dwordx4 v[160:163], v[4:5], off offset:768
	global_load_dwordx4 v[164:167], v[12:13], off offset:768
	global_load_dwordx4 v[168:171], v[14:15], off offset:768
	global_load_dwordx4 v[172:175], v[4:5], off offset:832
	global_load_dwordx4 v[176:179], v[12:13], off offset:832
	global_load_dwordx4 v[180:183], v[14:15], off offset:832
	global_load_dwordx4 v[184:187], v[4:5], off offset:896
	global_load_dwordx4 v[188:191], v[12:13], off offset:896
	global_load_dwordx4 v[192:195], v[14:15], off offset:896
	global_load_dwordx4 v[196:199], v[4:5], off offset:960
	global_load_dwordx4 v[200:203], v[12:13], off offset:960
	global_load_dwordx4 v[204:207], v[14:15], off offset:960
	s_waitcnt vmcnt(45)
	v_mfma_f32_16x16x32_bf16 v[208:211], v[20:23], v[16:19], v[208:211]
	v_mfma_f32_16x16x32_bf16 v[212:215], v[24:27], v[16:19], v[212:215]
	s_waitcnt vmcnt(42)
	v_mfma_f32_16x16x32_bf16 v[208:211], v[32:35], v[28:31], v[208:211]
	v_mfma_f32_16x16x32_bf16 v[212:215], v[36:39], v[28:31], v[212:215]
	s_waitcnt vmcnt(39)
	v_mfma_f32_16x16x32_bf16 v[208:211], v[44:47], v[40:43], v[208:211]
	v_mfma_f32_16x16x32_bf16 v[212:215], v[48:51], v[40:43], v[212:215]
	s_waitcnt vmcnt(36)
	v_mfma_f32_16x16x32_bf16 v[208:211], v[56:59], v[52:55], v[208:211]
	v_mfma_f32_16x16x32_bf16 v[212:215], v[60:63], v[52:55], v[212:215]
	s_waitcnt vmcnt(33)
	v_mfma_f32_16x16x32_bf16 v[208:211], v[68:71], v[64:67], v[208:211]
	v_mfma_f32_16x16x32_bf16 v[212:215], v[72:75], v[64:67], v[212:215]
	s_waitcnt vmcnt(30)
	v_mfma_f32_16x16x32_bf16 v[208:211], v[80:83], v[76:79], v[208:211]
	v_mfma_f32_16x16x32_bf16 v[212:215], v[84:87], v[76:79], v[212:215]
	s_waitcnt vmcnt(27)
	v_mfma_f32_16x16x32_bf16 v[208:211], v[92:95], v[88:91], v[208:211]
	v_mfma_f32_16x16x32_bf16 v[212:215], v[96:99], v[88:91], v[212:215]
	s_waitcnt vmcnt(24)
	v_mfma_f32_16x16x32_bf16 v[208:211], v[104:107], v[100:103], v[208:211]
	v_mfma_f32_16x16x32_bf16 v[212:215], v[108:111], v[100:103], v[212:215]
	s_waitcnt vmcnt(21)
	v_mfma_f32_16x16x32_bf16 v[208:211], v[116:119], v[112:115], v[208:211]
	v_mfma_f32_16x16x32_bf16 v[212:215], v[120:123], v[112:115], v[212:215]
	s_waitcnt vmcnt(18)
	v_mfma_f32_16x16x32_bf16 v[208:211], v[128:131], v[124:127], v[208:211]
	v_mfma_f32_16x16x32_bf16 v[212:215], v[132:135], v[124:127], v[212:215]
	s_waitcnt vmcnt(15)
	v_mfma_f32_16x16x32_bf16 v[208:211], v[140:143], v[136:139], v[208:211]
	v_mfma_f32_16x16x32_bf16 v[212:215], v[144:147], v[136:139], v[212:215]
	s_waitcnt vmcnt(12)
	v_mfma_f32_16x16x32_bf16 v[208:211], v[152:155], v[148:151], v[208:211]
	v_mfma_f32_16x16x32_bf16 v[212:215], v[156:159], v[148:151], v[212:215]
	s_waitcnt vmcnt(9)
	v_mfma_f32_16x16x32_bf16 v[208:211], v[164:167], v[160:163], v[208:211]
	v_mfma_f32_16x16x32_bf16 v[212:215], v[168:171], v[160:163], v[212:215]
	s_waitcnt vmcnt(6)
	v_mfma_f32_16x16x32_bf16 v[208:211], v[176:179], v[172:175], v[208:211]
	v_mfma_f32_16x16x32_bf16 v[212:215], v[180:183], v[172:175], v[212:215]
	s_waitcnt vmcnt(3)
	v_mfma_f32_16x16x32_bf16 v[208:211], v[188:191], v[184:187], v[208:211]
	v_mfma_f32_16x16x32_bf16 v[212:215], v[192:195], v[184:187], v[212:215]
	s_waitcnt vmcnt(0)
	v_mfma_f32_16x16x32_bf16 v[208:211], v[200:203], v[196:199], v[208:211]
	v_mfma_f32_16x16x32_bf16 v[212:215], v[204:207], v[196:199], v[212:215]
	global_load_dwordx4 v[16:19], v[4:5], off offset:1024
	global_load_dwordx4 v[20:23], v[12:13], off offset:1024
	global_load_dwordx4 v[24:27], v[14:15], off offset:1024
	global_load_dwordx4 v[28:31], v[4:5], off offset:1088
	global_load_dwordx4 v[32:35], v[12:13], off offset:1088
	global_load_dwordx4 v[36:39], v[14:15], off offset:1088
	global_load_dwordx4 v[40:43], v[4:5], off offset:1152
	global_load_dwordx4 v[44:47], v[12:13], off offset:1152
	global_load_dwordx4 v[48:51], v[14:15], off offset:1152
	global_load_dwordx4 v[52:55], v[4:5], off offset:1216
	global_load_dwordx4 v[56:59], v[12:13], off offset:1216
	global_load_dwordx4 v[60:63], v[14:15], off offset:1216
	global_load_dwordx4 v[64:67], v[4:5], off offset:1280
	global_load_dwordx4 v[68:71], v[12:13], off offset:1280
	global_load_dwordx4 v[72:75], v[14:15], off offset:1280
	global_load_dwordx4 v[76:79], v[4:5], off offset:1344
	global_load_dwordx4 v[80:83], v[12:13], off offset:1344
	global_load_dwordx4 v[84:87], v[14:15], off offset:1344
	global_load_dwordx4 v[88:91], v[4:5], off offset:1408
	global_load_dwordx4 v[92:95], v[12:13], off offset:1408
	global_load_dwordx4 v[96:99], v[14:15], off offset:1408
	global_load_dwordx4 v[100:103], v[4:5], off offset:1472
	global_load_dwordx4 v[104:107], v[12:13], off offset:1472
	global_load_dwordx4 v[108:111], v[14:15], off offset:1472
	global_load_dwordx4 v[112:115], v[4:5], off offset:1536
	global_load_dwordx4 v[116:119], v[12:13], off offset:1536
	global_load_dwordx4 v[120:123], v[14:15], off offset:1536
	global_load_dwordx4 v[124:127], v[4:5], off offset:1600
	global_load_dwordx4 v[128:131], v[12:13], off offset:1600
	global_load_dwordx4 v[132:135], v[14:15], off offset:1600
	global_load_dwordx4 v[136:139], v[4:5], off offset:1664
	global_load_dwordx4 v[140:143], v[12:13], off offset:1664
	global_load_dwordx4 v[144:147], v[14:15], off offset:1664
	global_load_dwordx4 v[148:151], v[4:5], off offset:1728
	global_load_dwordx4 v[152:155], v[12:13], off offset:1728
	global_load_dwordx4 v[156:159], v[14:15], off offset:1728
	global_load_dwordx4 v[160:163], v[4:5], off offset:1792
	global_load_dwordx4 v[164:167], v[12:13], off offset:1792
	global_load_dwordx4 v[168:171], v[14:15], off offset:1792
	global_load_dwordx4 v[172:175], v[4:5], off offset:1856
	global_load_dwordx4 v[176:179], v[12:13], off offset:1856
	global_load_dwordx4 v[180:183], v[14:15], off offset:1856
	global_load_dwordx4 v[184:187], v[4:5], off offset:1920
	global_load_dwordx4 v[188:191], v[12:13], off offset:1920
	global_load_dwordx4 v[192:195], v[14:15], off offset:1920
	global_load_dwordx4 v[196:199], v[4:5], off offset:1984
	global_load_dwordx4 v[200:203], v[12:13], off offset:1984
	global_load_dwordx4 v[204:207], v[14:15], off offset:1984
	s_waitcnt vmcnt(45)
	v_mfma_f32_16x16x32_bf16 v[208:211], v[20:23], v[16:19], v[208:211]
	v_mfma_f32_16x16x32_bf16 v[212:215], v[24:27], v[16:19], v[212:215]
	s_waitcnt vmcnt(42)
	v_mfma_f32_16x16x32_bf16 v[208:211], v[32:35], v[28:31], v[208:211]
	v_mfma_f32_16x16x32_bf16 v[212:215], v[36:39], v[28:31], v[212:215]
	s_waitcnt vmcnt(39)
	v_mfma_f32_16x16x32_bf16 v[208:211], v[44:47], v[40:43], v[208:211]
	v_mfma_f32_16x16x32_bf16 v[212:215], v[48:51], v[40:43], v[212:215]
	s_waitcnt vmcnt(36)
	v_mfma_f32_16x16x32_bf16 v[208:211], v[56:59], v[52:55], v[208:211]
	v_mfma_f32_16x16x32_bf16 v[212:215], v[60:63], v[52:55], v[212:215]
	s_waitcnt vmcnt(33)
	v_mfma_f32_16x16x32_bf16 v[208:211], v[68:71], v[64:67], v[208:211]
	v_mfma_f32_16x16x32_bf16 v[212:215], v[72:75], v[64:67], v[212:215]
	s_waitcnt vmcnt(30)
	v_mfma_f32_16x16x32_bf16 v[208:211], v[80:83], v[76:79], v[208:211]
	v_mfma_f32_16x16x32_bf16 v[212:215], v[84:87], v[76:79], v[212:215]
	s_waitcnt vmcnt(27)
	v_mfma_f32_16x16x32_bf16 v[208:211], v[92:95], v[88:91], v[208:211]
	v_mfma_f32_16x16x32_bf16 v[212:215], v[96:99], v[88:91], v[212:215]
	s_waitcnt vmcnt(24)
	v_mfma_f32_16x16x32_bf16 v[208:211], v[104:107], v[100:103], v[208:211]
	v_mfma_f32_16x16x32_bf16 v[212:215], v[108:111], v[100:103], v[212:215]
	s_waitcnt vmcnt(21)
	v_mfma_f32_16x16x32_bf16 v[208:211], v[116:119], v[112:115], v[208:211]
	v_mfma_f32_16x16x32_bf16 v[212:215], v[120:123], v[112:115], v[212:215]
	s_waitcnt vmcnt(18)
	v_mfma_f32_16x16x32_bf16 v[208:211], v[128:131], v[124:127], v[208:211]
	v_mfma_f32_16x16x32_bf16 v[212:215], v[132:135], v[124:127], v[212:215]
	s_waitcnt vmcnt(15)
	v_mfma_f32_16x16x32_bf16 v[208:211], v[140:143], v[136:139], v[208:211]
	v_mfma_f32_16x16x32_bf16 v[212:215], v[144:147], v[136:139], v[212:215]
	s_waitcnt vmcnt(12)
	v_mfma_f32_16x16x32_bf16 v[208:211], v[152:155], v[148:151], v[208:211]
	v_mfma_f32_16x16x32_bf16 v[212:215], v[156:159], v[148:151], v[212:215]
	s_waitcnt vmcnt(9)
	v_mfma_f32_16x16x32_bf16 v[208:211], v[164:167], v[160:163], v[208:211]
	v_mfma_f32_16x16x32_bf16 v[212:215], v[168:171], v[160:163], v[212:215]
	s_waitcnt vmcnt(6)
	v_mfma_f32_16x16x32_bf16 v[208:211], v[176:179], v[172:175], v[208:211]
	v_mfma_f32_16x16x32_bf16 v[212:215], v[180:183], v[172:175], v[212:215]
	s_waitcnt vmcnt(3)
	v_mfma_f32_16x16x32_bf16 v[208:211], v[188:191], v[184:187], v[208:211]
	v_mfma_f32_16x16x32_bf16 v[212:215], v[192:195], v[184:187], v[212:215]
	s_waitcnt vmcnt(0)
	v_mfma_f32_16x16x32_bf16 v[208:211], v[200:203], v[196:199], v[208:211]
	v_mfma_f32_16x16x32_bf16 v[212:215], v[204:207], v[196:199], v[212:215]
	v_add_f32_e32 v216, v216, v217
	v_add_f32_e32 v218, v218, v219
	v_add_f32_e32 v216, v216, v218
	v_mov_b32_e32 v217, v216
	s_nop 1
	v_permlane16_swap_b32_e32 v217, v216
	s_nop 1
	v_add_f32_e32 v216, v216, v217
	v_mov_b32_e32 v217, v216
	s_nop 1
	v_permlane32_swap_b32_e32 v217, v216
	s_nop 1
	v_add_f32_e32 v216, v216, v217
	v_mov_b32_e32 v229, 0x358637bd
	v_fmamk_f32 v216, v216, 0x3a800000, v229
	v_rsq_f32_e32 v228, v216
	s_waitcnt lgkmcnt(0)
	v_lshl_add_u64 v[246:247], s[12:13], 0, v[6:7]
	s_nop 3
	v_pk_mul_f32 v[208:209], v[208:209], v[228:229] op_sel_hi:[1,0]
	v_pk_mul_f32 v[210:211], v[210:211], v[228:229] op_sel_hi:[1,0]
	v_pk_mul_f32 v[212:213], v[212:213], v[228:229] op_sel_hi:[1,0]
	v_pk_mul_f32 v[214:215], v[214:215], v[228:229] op_sel_hi:[1,0]
	v_mul_f32_e32 v208, 0xbfb8aa3b, v208
	v_mul_f32_e32 v209, 0xbfb8aa3b, v209
	v_mul_f32_e32 v210, 0xbfb8aa3b, v210
	v_mul_f32_e32 v211, 0xbfb8aa3b, v211
	v_mul_f32_e32 v212, 0xbfb8aa3b, v212
	v_mul_f32_e32 v213, 0xbfb8aa3b, v213
	v_mul_f32_e32 v214, 0xbfb8aa3b, v214
	v_mul_f32_e32 v215, 0xbfb8aa3b, v215
	v_exp_f32_e32 v208, v208
	v_exp_f32_e32 v209, v209
	v_exp_f32_e32 v210, v210
	v_exp_f32_e32 v211, v211
	v_exp_f32_e32 v212, v212
	v_exp_f32_e32 v213, v213
	v_exp_f32_e32 v214, v214
	v_exp_f32_e32 v215, v215
	v_add_f32_e32 v208, 1.0, v208
	v_add_f32_e32 v209, 1.0, v209
	v_add_f32_e32 v210, 1.0, v210
	v_add_f32_e32 v211, 1.0, v211
	v_add_f32_e32 v212, 1.0, v212
	v_add_f32_e32 v213, 1.0, v213
	v_add_f32_e32 v214, 1.0, v214
	v_add_f32_e32 v215, 1.0, v215
	v_rcp_f32_e32 v208, v208
	v_rcp_f32_e32 v209, v209
	v_rcp_f32_e32 v210, v210
	v_rcp_f32_e32 v211, v211
	v_rcp_f32_e32 v212, v212
	v_rcp_f32_e32 v213, v213
	v_rcp_f32_e32 v214, v214
	v_rcp_f32_e32 v215, v215
	v_lshlrev_b32_e32 v230, 16, v220
	v_and_b32_e32 v231, 0xffff0000, v220
	v_lshlrev_b32_e32 v238, 16, v224
	v_and_b32_e32 v239, 0xffff0000, v224
	v_lshlrev_b32_e32 v232, 16, v221
	v_and_b32_e32 v233, 0xffff0000, v221
	v_lshlrev_b32_e32 v240, 16, v225
	v_and_b32_e32 v241, 0xffff0000, v225
	v_lshlrev_b32_e32 v234, 16, v222
	v_and_b32_e32 v235, 0xffff0000, v222
	v_lshlrev_b32_e32 v242, 16, v226
	v_and_b32_e32 v243, 0xffff0000, v226
	v_lshlrev_b32_e32 v236, 16, v223
	v_and_b32_e32 v237, 0xffff0000, v223
	v_lshlrev_b32_e32 v244, 16, v227
	v_and_b32_e32 v245, 0xffff0000, v227
	v_pk_fma_f32 v[208:209], v[208:209], v[238:239], v[230:231]
	v_pk_fma_f32 v[210:211], v[210:211], v[240:241], v[232:233]
	v_pk_fma_f32 v[212:213], v[212:213], v[242:243], v[234:235]
	v_pk_fma_f32 v[214:215], v[214:215], v[244:245], v[236:237]
	global_store_dwordx4 v[246:247], v[208:211], off nt
	global_store_dwordx4 v[246:247], v[212:215], off offset:16 nt
